# v16 with the static GEMM K-loop priority on the LEADING half instead of the trailing half (mirror test)
# baseline (speedup 1.0000x reference)
.LBB0_212:
	s_ashr_i32 s47, s46, 31
	s_lshl_b64 s[8:9], s[46:47], 20
	s_add_u32 s48, s30, s8
	s_addc_u32 s49, s31, s9
	s_and_b64 s[8:9], s[2:3], exec
	s_cselect_b32 s8, s49, s85
	s_cselect_b32 s9, s48, s84
	s_ashr_i32 s45, s44, 31
	s_lshl_b64 s[12:13], s[44:45], 20
	s_add_u32 s50, s14, s12
	s_addc_u32 s51, s15, s13
	s_and_b64 s[12:13], s[2:3], exec
	s_cselect_b32 s12, s51, s87
	s_cselect_b32 s13, s50, s86
	s_add_u32 s84, s84, 0x80080
	s_addc_u32 s85, s85, 0
	s_add_u32 s16, s86, 0x100
	v_mov_b32_e32 v2, 0
	s_addc_u32 s17, s87, 0
	s_mov_b32 s18, -2
	v_mov_b32_e32 v3, v2
	v_mov_b32_e32 v4, v2
	v_mov_b32_e32 v5, v2
	v_mov_b32_e32 v6, v2
	v_mov_b32_e32 v7, v2
	v_mov_b32_e32 v8, v2
	v_mov_b32_e32 v9, v2
	v_mov_b32_e32 v18, v2
	v_mov_b32_e32 v19, v2
	v_mov_b32_e32 v20, v2
	v_mov_b32_e32 v21, v2
	v_mov_b32_e32 v22, v2
	v_mov_b32_e32 v23, v2
	v_mov_b32_e32 v24, v2
	v_mov_b32_e32 v25, v2
	v_mov_b32_e32 v34, v2
	v_mov_b32_e32 v35, v2
	v_mov_b32_e32 v36, v2
	v_mov_b32_e32 v37, v2
	v_mov_b32_e32 v38, v2
	v_mov_b32_e32 v39, v2
	v_mov_b32_e32 v40, v2
	v_mov_b32_e32 v41, v2
	v_mov_b32_e32 v50, v2
	v_mov_b32_e32 v51, v2
	v_mov_b32_e32 v52, v2
	v_mov_b32_e32 v53, v2
	v_mov_b32_e32 v54, v2
	v_mov_b32_e32 v55, v2
	v_mov_b32_e32 v56, v2
	v_mov_b32_e32 v57, v2
	v_mov_b32_e32 v10, v2
	v_mov_b32_e32 v11, v2
	v_mov_b32_e32 v12, v2
	v_mov_b32_e32 v13, v2
	v_mov_b32_e32 v14, v2
	v_mov_b32_e32 v15, v2
	v_mov_b32_e32 v16, v2
	v_mov_b32_e32 v17, v2
	v_mov_b32_e32 v26, v2
	v_mov_b32_e32 v27, v2
	v_mov_b32_e32 v28, v2
	v_mov_b32_e32 v29, v2
	v_mov_b32_e32 v30, v2
	v_mov_b32_e32 v31, v2
	v_mov_b32_e32 v32, v2
	v_mov_b32_e32 v33, v2
	v_mov_b32_e32 v42, v2
	v_mov_b32_e32 v43, v2
	v_mov_b32_e32 v44, v2
	v_mov_b32_e32 v45, v2
	v_mov_b32_e32 v46, v2
	v_mov_b32_e32 v47, v2
	v_mov_b32_e32 v48, v2
	v_mov_b32_e32 v49, v2
	v_mov_b32_e32 v58, v2
	v_mov_b32_e32 v59, v2
	v_mov_b32_e32 v60, v2
	v_mov_b32_e32 v61, v2
	v_mov_b32_e32 v62, v2
	v_mov_b32_e32 v63, v2
	v_mov_b32_e32 v64, v2
	v_mov_b32_e32 v65, v2
	v_mov_b32_e32 v66, v2
	v_mov_b32_e32 v67, v2
	v_mov_b32_e32 v68, v2
	v_mov_b32_e32 v69, v2
	v_mov_b32_e32 v70, v2
	v_mov_b32_e32 v71, v2
	v_mov_b32_e32 v72, v2
	v_mov_b32_e32 v73, v2
	v_mov_b32_e32 v82, v2
	v_mov_b32_e32 v83, v2
	v_mov_b32_e32 v84, v2
	v_mov_b32_e32 v85, v2
	v_mov_b32_e32 v86, v2
	v_mov_b32_e32 v87, v2
	v_mov_b32_e32 v88, v2
	v_mov_b32_e32 v89, v2
	v_mov_b32_e32 v98, v2
	v_mov_b32_e32 v99, v2
	v_mov_b32_e32 v100, v2
	v_mov_b32_e32 v101, v2
	v_mov_b32_e32 v102, v2
	v_mov_b32_e32 v103, v2
	v_mov_b32_e32 v104, v2
	v_mov_b32_e32 v105, v2
	v_mov_b32_e32 v114, v2
	v_mov_b32_e32 v115, v2
	v_mov_b32_e32 v116, v2
	v_mov_b32_e32 v117, v2
	v_mov_b32_e32 v118, v2
	v_mov_b32_e32 v119, v2
	v_mov_b32_e32 v120, v2
	v_mov_b32_e32 v121, v2
	v_mov_b32_e32 v74, v2
	v_mov_b32_e32 v75, v2
	v_mov_b32_e32 v76, v2
	v_mov_b32_e32 v77, v2
	v_mov_b32_e32 v78, v2
	v_mov_b32_e32 v79, v2
	v_mov_b32_e32 v80, v2
	v_mov_b32_e32 v81, v2
	v_mov_b32_e32 v90, v2
	v_mov_b32_e32 v91, v2
	v_mov_b32_e32 v92, v2
	v_mov_b32_e32 v93, v2
	v_mov_b32_e32 v94, v2
	v_mov_b32_e32 v95, v2
	v_mov_b32_e32 v96, v2
	v_mov_b32_e32 v97, v2
	v_mov_b32_e32 v106, v2
	v_mov_b32_e32 v107, v2
	v_mov_b32_e32 v108, v2
	v_mov_b32_e32 v109, v2
	v_mov_b32_e32 v110, v2
	v_mov_b32_e32 v111, v2
	v_mov_b32_e32 v112, v2
	v_mov_b32_e32 v113, v2
	v_mov_b32_e32 v122, v2
	v_mov_b32_e32 v123, v2
	v_mov_b32_e32 v124, v2
	v_mov_b32_e32 v125, v2
	v_mov_b32_e32 v126, v2
	v_mov_b32_e32 v127, v2
	v_mov_b32_e32 v128, v2
	v_mov_b32_e32 v129, v2
	s_and_b64 vcc, exec, s[6:7]
	s_cbranch_vccz .Lsp_p2
	s_setprio 1

.LBB0_361:
	s_add_u32 s6, s6, 0x158080
	s_addc_u32 s7, s7, 0
	s_add_u32 s8, s82, 0x100
	v_mov_b32_e32 v2, 0
	s_addc_u32 s12, s83, 0
	s_mov_b32 s13, -2
	v_mov_b32_e32 v3, v2
	v_mov_b32_e32 v4, v2
	v_mov_b32_e32 v5, v2
	v_mov_b32_e32 v6, v2
	v_mov_b32_e32 v7, v2
	v_mov_b32_e32 v8, v2
	v_mov_b32_e32 v9, v2
	v_mov_b32_e32 v18, v2
	v_mov_b32_e32 v19, v2
	v_mov_b32_e32 v20, v2
	v_mov_b32_e32 v21, v2
	v_mov_b32_e32 v22, v2
	v_mov_b32_e32 v23, v2
	v_mov_b32_e32 v24, v2
	v_mov_b32_e32 v25, v2
	v_mov_b32_e32 v34, v2
	v_mov_b32_e32 v35, v2
	v_mov_b32_e32 v36, v2
	v_mov_b32_e32 v37, v2
	v_mov_b32_e32 v38, v2
	v_mov_b32_e32 v39, v2
	v_mov_b32_e32 v40, v2
	v_mov_b32_e32 v41, v2
	v_mov_b32_e32 v50, v2
	v_mov_b32_e32 v51, v2
	v_mov_b32_e32 v52, v2
	v_mov_b32_e32 v53, v2
	v_mov_b32_e32 v54, v2
	v_mov_b32_e32 v55, v2
	v_mov_b32_e32 v56, v2
	v_mov_b32_e32 v57, v2
	v_mov_b32_e32 v10, v2
	v_mov_b32_e32 v11, v2
	v_mov_b32_e32 v12, v2
	v_mov_b32_e32 v13, v2
	v_mov_b32_e32 v14, v2
	v_mov_b32_e32 v15, v2
	v_mov_b32_e32 v16, v2
	v_mov_b32_e32 v17, v2
	v_mov_b32_e32 v26, v2
	v_mov_b32_e32 v27, v2
	v_mov_b32_e32 v28, v2
	v_mov_b32_e32 v29, v2
	v_mov_b32_e32 v30, v2
	v_mov_b32_e32 v31, v2
	v_mov_b32_e32 v32, v2
	v_mov_b32_e32 v33, v2
	v_mov_b32_e32 v42, v2
	v_mov_b32_e32 v43, v2
	v_mov_b32_e32 v44, v2
	v_mov_b32_e32 v45, v2
	v_mov_b32_e32 v46, v2
	v_mov_b32_e32 v47, v2
	v_mov_b32_e32 v48, v2
	v_mov_b32_e32 v49, v2
	v_mov_b32_e32 v58, v2
	v_mov_b32_e32 v59, v2
	v_mov_b32_e32 v60, v2
	v_mov_b32_e32 v61, v2
	v_mov_b32_e32 v62, v2
	v_mov_b32_e32 v63, v2
	v_mov_b32_e32 v64, v2
	v_mov_b32_e32 v65, v2
	v_mov_b32_e32 v66, v2
	v_mov_b32_e32 v67, v2
	v_mov_b32_e32 v68, v2
	v_mov_b32_e32 v69, v2
	v_mov_b32_e32 v70, v2
	v_mov_b32_e32 v71, v2
	v_mov_b32_e32 v72, v2
	v_mov_b32_e32 v73, v2
	v_mov_b32_e32 v82, v2
	v_mov_b32_e32 v83, v2
	v_mov_b32_e32 v84, v2
	v_mov_b32_e32 v85, v2
	v_mov_b32_e32 v86, v2
	v_mov_b32_e32 v87, v2
	v_mov_b32_e32 v88, v2
	v_mov_b32_e32 v89, v2
	v_mov_b32_e32 v98, v2
	v_mov_b32_e32 v99, v2
	v_mov_b32_e32 v100, v2
	v_mov_b32_e32 v101, v2
	v_mov_b32_e32 v102, v2
	v_mov_b32_e32 v103, v2
	v_mov_b32_e32 v104, v2
	v_mov_b32_e32 v105, v2
	v_mov_b32_e32 v130, v2
	v_mov_b32_e32 v131, v2
	v_mov_b32_e32 v132, v2
	v_mov_b32_e32 v133, v2
	v_mov_b32_e32 v134, v2
	v_mov_b32_e32 v135, v2
	v_mov_b32_e32 v136, v2
	v_mov_b32_e32 v137, v2
	v_mov_b32_e32 v74, v2
	v_mov_b32_e32 v75, v2
	v_mov_b32_e32 v76, v2
	v_mov_b32_e32 v77, v2
	v_mov_b32_e32 v78, v2
	v_mov_b32_e32 v79, v2
	v_mov_b32_e32 v80, v2
	v_mov_b32_e32 v81, v2
	v_mov_b32_e32 v90, v2
	v_mov_b32_e32 v91, v2
	v_mov_b32_e32 v92, v2
	v_mov_b32_e32 v93, v2
	v_mov_b32_e32 v94, v2
	v_mov_b32_e32 v95, v2
	v_mov_b32_e32 v96, v2
	v_mov_b32_e32 v97, v2
	v_mov_b32_e32 v118, v2
	v_mov_b32_e32 v119, v2
	v_mov_b32_e32 v120, v2
	v_mov_b32_e32 v121, v2
	v_mov_b32_e32 v126, v2
	v_mov_b32_e32 v127, v2
	v_mov_b32_e32 v128, v2
	v_mov_b32_e32 v129, v2
	v_mov_b32_e32 v138, v2
	v_mov_b32_e32 v139, v2
	v_mov_b32_e32 v140, v2
	v_mov_b32_e32 v141, v2
	v_mov_b32_e32 v142, v2
	v_mov_b32_e32 v143, v2
	v_mov_b32_e32 v144, v2
	v_mov_b32_e32 v145, v2
	s_and_b64 vcc, exec, s[46:47]
	s_cbranch_vccz .Lsp_p3
	s_setprio 1

.LBB0_540:
	s_ashr_i32 s49, s48, 31
	s_lshl_b64 s[8:9], s[48:49], 21
	s_add_u32 s50, s78, s8
	s_addc_u32 s51, s79, s9
	s_and_b64 s[8:9], s[2:3], exec
	s_cselect_b32 s5, s51, s85
	s_cselect_b32 s8, s50, s84
	s_ashr_i32 s47, s46, 31
	s_lshl_b64 s[12:13], s[46:47], 21
	s_add_u32 s80, s76, s12
	s_addc_u32 s81, s77, s13
	s_and_b64 s[12:13], s[2:3], exec
	s_cselect_b32 s9, s81, s87
	s_cselect_b32 s12, s80, s86
	s_add_u32 s84, s84, 0x100080
	s_addc_u32 s85, s85, 0
	s_add_u32 s13, s86, 0x100
	v_mov_b32_e32 v2, 0
	s_addc_u32 s16, s87, 0
	s_mov_b32 s17, -2
	v_mov_b32_e32 v3, v2
	v_mov_b32_e32 v4, v2
	v_mov_b32_e32 v5, v2
	v_mov_b32_e32 v6, v2
	v_mov_b32_e32 v7, v2
	v_mov_b32_e32 v8, v2
	v_mov_b32_e32 v9, v2
	v_mov_b32_e32 v18, v2
	v_mov_b32_e32 v19, v2
	v_mov_b32_e32 v20, v2
	v_mov_b32_e32 v21, v2
	v_mov_b32_e32 v22, v2
	v_mov_b32_e32 v23, v2
	v_mov_b32_e32 v24, v2
	v_mov_b32_e32 v25, v2
	v_mov_b32_e32 v34, v2
	v_mov_b32_e32 v35, v2
	v_mov_b32_e32 v36, v2
	v_mov_b32_e32 v37, v2
	v_mov_b32_e32 v38, v2
	v_mov_b32_e32 v39, v2
	v_mov_b32_e32 v40, v2
	v_mov_b32_e32 v41, v2
	v_mov_b32_e32 v50, v2
	v_mov_b32_e32 v51, v2
	v_mov_b32_e32 v52, v2
	v_mov_b32_e32 v53, v2
	v_mov_b32_e32 v54, v2
	v_mov_b32_e32 v55, v2
	v_mov_b32_e32 v56, v2
	v_mov_b32_e32 v57, v2
	v_mov_b32_e32 v10, v2
	v_mov_b32_e32 v11, v2
	v_mov_b32_e32 v12, v2
	v_mov_b32_e32 v13, v2
	v_mov_b32_e32 v14, v2
	v_mov_b32_e32 v15, v2
	v_mov_b32_e32 v16, v2
	v_mov_b32_e32 v17, v2
	v_mov_b32_e32 v26, v2
	v_mov_b32_e32 v27, v2
	v_mov_b32_e32 v28, v2
	v_mov_b32_e32 v29, v2
	v_mov_b32_e32 v30, v2
	v_mov_b32_e32 v31, v2
	v_mov_b32_e32 v32, v2
	v_mov_b32_e32 v33, v2
	v_mov_b32_e32 v42, v2
	v_mov_b32_e32 v43, v2
	v_mov_b32_e32 v44, v2
	v_mov_b32_e32 v45, v2
	v_mov_b32_e32 v46, v2
	v_mov_b32_e32 v47, v2
	v_mov_b32_e32 v48, v2
	v_mov_b32_e32 v49, v2
	v_mov_b32_e32 v58, v2
	v_mov_b32_e32 v59, v2
	v_mov_b32_e32 v60, v2
	v_mov_b32_e32 v61, v2
	v_mov_b32_e32 v62, v2
	v_mov_b32_e32 v63, v2
	v_mov_b32_e32 v64, v2
	v_mov_b32_e32 v65, v2
	v_mov_b32_e32 v66, v2
	v_mov_b32_e32 v67, v2
	v_mov_b32_e32 v68, v2
	v_mov_b32_e32 v69, v2
	v_mov_b32_e32 v70, v2
	v_mov_b32_e32 v71, v2
	v_mov_b32_e32 v72, v2
	v_mov_b32_e32 v73, v2
	v_mov_b32_e32 v82, v2
	v_mov_b32_e32 v83, v2
	v_mov_b32_e32 v84, v2
	v_mov_b32_e32 v85, v2
	v_mov_b32_e32 v86, v2
	v_mov_b32_e32 v87, v2
	v_mov_b32_e32 v88, v2
	v_mov_b32_e32 v89, v2
	v_mov_b32_e32 v98, v2
	v_mov_b32_e32 v99, v2
	v_mov_b32_e32 v100, v2
	v_mov_b32_e32 v101, v2
	v_mov_b32_e32 v102, v2
	v_mov_b32_e32 v103, v2
	v_mov_b32_e32 v104, v2
	v_mov_b32_e32 v105, v2
	v_mov_b32_e32 v114, v2
	v_mov_b32_e32 v115, v2
	v_mov_b32_e32 v116, v2
	v_mov_b32_e32 v117, v2
	v_mov_b32_e32 v118, v2
	v_mov_b32_e32 v119, v2
	v_mov_b32_e32 v120, v2
	v_mov_b32_e32 v121, v2
	v_mov_b32_e32 v74, v2
	v_mov_b32_e32 v75, v2
	v_mov_b32_e32 v76, v2
	v_mov_b32_e32 v77, v2
	v_mov_b32_e32 v78, v2
	v_mov_b32_e32 v79, v2
	v_mov_b32_e32 v80, v2
	v_mov_b32_e32 v81, v2
	v_mov_b32_e32 v90, v2
	v_mov_b32_e32 v91, v2
	v_mov_b32_e32 v92, v2
	v_mov_b32_e32 v93, v2
	v_mov_b32_e32 v94, v2
	v_mov_b32_e32 v95, v2
	v_mov_b32_e32 v96, v2
	v_mov_b32_e32 v97, v2
	v_mov_b32_e32 v106, v2
	v_mov_b32_e32 v107, v2
	v_mov_b32_e32 v108, v2
	v_mov_b32_e32 v109, v2
	v_mov_b32_e32 v110, v2
	v_mov_b32_e32 v111, v2
	v_mov_b32_e32 v112, v2
	v_mov_b32_e32 v113, v2
	v_mov_b32_e32 v122, v2
	v_mov_b32_e32 v123, v2
	v_mov_b32_e32 v124, v2
	v_mov_b32_e32 v125, v2
	v_mov_b32_e32 v126, v2
	v_mov_b32_e32 v127, v2
	v_mov_b32_e32 v128, v2
	v_mov_b32_e32 v129, v2
	s_and_b64 vcc, exec, s[42:43]
	s_cbranch_vccz .Lsp_p5
	s_setprio 1

.LBB0_885:
	s_ashr_i32 s41, s40, 31
	s_lshl_b64 s[8:9], s[40:41], 21
	s_add_u32 s42, s30, s8
	s_addc_u32 s43, s31, s9
	s_and_b64 s[8:9], s[2:3], exec
	s_cselect_b32 s8, s43, s49
	s_cselect_b32 s9, s42, s48
	s_ashr_i32 s29, s28, 31
	s_lshl_b64 s[12:13], s[28:29], 21
	s_add_u32 s44, s72, s12
	s_addc_u32 s45, s73, s13
	s_and_b64 s[12:13], s[2:3], exec
	s_cselect_b32 s12, s45, s51
	s_cselect_b32 s13, s44, s50
	s_add_u32 s48, s48, 0x100080
	s_addc_u32 s49, s49, 0
	s_add_u32 s29, s50, 0x100
	v_mov_b32_e32 v2, 0
	s_addc_u32 s41, s51, 0
	s_mov_b32 s78, -2
	v_mov_b32_e32 v3, v2
	v_mov_b32_e32 v4, v2
	v_mov_b32_e32 v5, v2
	v_mov_b32_e32 v6, v2
	v_mov_b32_e32 v7, v2
	v_mov_b32_e32 v8, v2
	v_mov_b32_e32 v9, v2
	v_mov_b32_e32 v10, v2
	v_mov_b32_e32 v11, v2
	v_mov_b32_e32 v12, v2
	v_mov_b32_e32 v13, v2
	v_mov_b32_e32 v18, v2
	v_mov_b32_e32 v19, v2
	v_mov_b32_e32 v20, v2
	v_mov_b32_e32 v21, v2
	v_mov_b32_e32 v26, v2
	v_mov_b32_e32 v27, v2
	v_mov_b32_e32 v28, v2
	v_mov_b32_e32 v29, v2
	v_mov_b32_e32 v34, v2
	v_mov_b32_e32 v35, v2
	v_mov_b32_e32 v36, v2
	v_mov_b32_e32 v37, v2
	v_mov_b32_e32 v42, v2
	v_mov_b32_e32 v43, v2
	v_mov_b32_e32 v44, v2
	v_mov_b32_e32 v45, v2
	v_mov_b32_e32 v50, v2
	v_mov_b32_e32 v51, v2
	v_mov_b32_e32 v52, v2
	v_mov_b32_e32 v53, v2
	v_mov_b32_e32 v14, v2
	v_mov_b32_e32 v15, v2
	v_mov_b32_e32 v16, v2
	v_mov_b32_e32 v17, v2
	v_mov_b32_e32 v22, v2
	v_mov_b32_e32 v23, v2
	v_mov_b32_e32 v24, v2
	v_mov_b32_e32 v25, v2
	v_mov_b32_e32 v30, v2
	v_mov_b32_e32 v31, v2
	v_mov_b32_e32 v32, v2
	v_mov_b32_e32 v33, v2
	v_mov_b32_e32 v38, v2
	v_mov_b32_e32 v39, v2
	v_mov_b32_e32 v40, v2
	v_mov_b32_e32 v41, v2
	v_mov_b32_e32 v46, v2
	v_mov_b32_e32 v47, v2
	v_mov_b32_e32 v48, v2
	v_mov_b32_e32 v49, v2
	v_mov_b32_e32 v54, v2
	v_mov_b32_e32 v55, v2
	v_mov_b32_e32 v56, v2
	v_mov_b32_e32 v57, v2
	v_mov_b32_e32 v58, v2
	v_mov_b32_e32 v59, v2
	v_mov_b32_e32 v60, v2
	v_mov_b32_e32 v61, v2
	v_mov_b32_e32 v62, v2
	v_mov_b32_e32 v63, v2
	v_mov_b32_e32 v64, v2
	v_mov_b32_e32 v65, v2
	v_mov_b32_e32 v66, v2
	v_mov_b32_e32 v67, v2
	v_mov_b32_e32 v68, v2
	v_mov_b32_e32 v69, v2
	v_mov_b32_e32 v70, v2
	v_mov_b32_e32 v71, v2
	v_mov_b32_e32 v72, v2
	v_mov_b32_e32 v73, v2
	v_mov_b32_e32 v74, v2
	v_mov_b32_e32 v75, v2
	v_mov_b32_e32 v76, v2
	v_mov_b32_e32 v77, v2
	v_mov_b32_e32 v82, v2
	v_mov_b32_e32 v83, v2
	v_mov_b32_e32 v84, v2
	v_mov_b32_e32 v85, v2
	v_mov_b32_e32 v90, v2
	v_mov_b32_e32 v91, v2
	v_mov_b32_e32 v92, v2
	v_mov_b32_e32 v93, v2
	v_mov_b32_e32 v98, v2
	v_mov_b32_e32 v99, v2
	v_mov_b32_e32 v100, v2
	v_mov_b32_e32 v101, v2
	v_mov_b32_e32 v106, v2
	v_mov_b32_e32 v107, v2
	v_mov_b32_e32 v108, v2
	v_mov_b32_e32 v109, v2
	v_mov_b32_e32 v114, v2
	v_mov_b32_e32 v115, v2
	v_mov_b32_e32 v116, v2
	v_mov_b32_e32 v117, v2
	v_mov_b32_e32 v78, v2
	v_mov_b32_e32 v79, v2
	v_mov_b32_e32 v80, v2
	v_mov_b32_e32 v81, v2
	v_mov_b32_e32 v86, v2
	v_mov_b32_e32 v87, v2
	v_mov_b32_e32 v88, v2
	v_mov_b32_e32 v89, v2
	v_mov_b32_e32 v94, v2
	v_mov_b32_e32 v95, v2
	v_mov_b32_e32 v96, v2
	v_mov_b32_e32 v97, v2
	v_mov_b32_e32 v102, v2
	v_mov_b32_e32 v103, v2
	v_mov_b32_e32 v104, v2
	v_mov_b32_e32 v105, v2
	v_mov_b32_e32 v110, v2
	v_mov_b32_e32 v111, v2
	v_mov_b32_e32 v112, v2
	v_mov_b32_e32 v113, v2
	v_mov_b32_e32 v118, v2
	v_mov_b32_e32 v119, v2
	v_mov_b32_e32 v120, v2
	v_mov_b32_e32 v121, v2
	v_mov_b32_e32 v122, v2
	v_mov_b32_e32 v123, v2
	v_mov_b32_e32 v124, v2
	v_mov_b32_e32 v125, v2
	v_mov_b32_e32 v126, v2
	v_mov_b32_e32 v127, v2
	v_mov_b32_e32 v128, v2
	v_mov_b32_e32 v129, v2
	s_and_b64 vcc, exec, s[18:19]
	s_cbranch_vccz .Lsp_p9
	s_setprio 1

.LBB0_1014:
	s_ashr_i32 s23, s22, 31
	s_lshl_b64 s[8:9], s[22:23], 20
	s_add_u32 s24, s30, s8
	s_addc_u32 s25, s31, s9
	s_and_b64 s[8:9], s[2:3], exec
	s_cselect_b32 s8, s25, s43
	s_cselect_b32 s9, s24, s42
	s_ashr_i32 s21, s20, 31
	s_lshl_b64 s[28:29], s[20:21], 20
	s_add_u32 s28, s14, s28
	s_addc_u32 s29, s15, s29
	s_and_b64 s[46:47], s[2:3], exec
	s_cselect_b32 s21, s29, s45
	s_cselect_b32 s23, s28, s44
	s_add_u32 s42, s42, 0x80080
	s_addc_u32 s43, s43, 0
	s_add_u32 s61, s44, 0x100
	v_mov_b32_e32 v2, 0
	s_addc_u32 s66, s45, 0
	s_mov_b32 s67, -2
	v_mov_b32_e32 v3, v2
	v_mov_b32_e32 v4, v2
	v_mov_b32_e32 v5, v2
	v_mov_b32_e32 v6, v2
	v_mov_b32_e32 v7, v2
	v_mov_b32_e32 v8, v2
	v_mov_b32_e32 v9, v2
	v_mov_b32_e32 v18, v2
	v_mov_b32_e32 v19, v2
	v_mov_b32_e32 v20, v2
	v_mov_b32_e32 v21, v2
	v_mov_b32_e32 v22, v2
	v_mov_b32_e32 v23, v2
	v_mov_b32_e32 v24, v2
	v_mov_b32_e32 v25, v2
	v_mov_b32_e32 v34, v2
	v_mov_b32_e32 v35, v2
	v_mov_b32_e32 v36, v2
	v_mov_b32_e32 v37, v2
	v_mov_b32_e32 v38, v2
	v_mov_b32_e32 v39, v2
	v_mov_b32_e32 v40, v2
	v_mov_b32_e32 v41, v2
	v_mov_b32_e32 v50, v2
	v_mov_b32_e32 v51, v2
	v_mov_b32_e32 v52, v2
	v_mov_b32_e32 v53, v2
	v_mov_b32_e32 v54, v2
	v_mov_b32_e32 v55, v2
	v_mov_b32_e32 v56, v2
	v_mov_b32_e32 v57, v2
	v_mov_b32_e32 v10, v2
	v_mov_b32_e32 v11, v2
	v_mov_b32_e32 v12, v2
	v_mov_b32_e32 v13, v2
	v_mov_b32_e32 v14, v2
	v_mov_b32_e32 v15, v2
	v_mov_b32_e32 v16, v2
	v_mov_b32_e32 v17, v2
	v_mov_b32_e32 v26, v2
	v_mov_b32_e32 v27, v2
	v_mov_b32_e32 v28, v2
	v_mov_b32_e32 v29, v2
	v_mov_b32_e32 v30, v2
	v_mov_b32_e32 v31, v2
	v_mov_b32_e32 v32, v2
	v_mov_b32_e32 v33, v2
	v_mov_b32_e32 v42, v2
	v_mov_b32_e32 v43, v2
	v_mov_b32_e32 v44, v2
	v_mov_b32_e32 v45, v2
	v_mov_b32_e32 v46, v2
	v_mov_b32_e32 v47, v2
	v_mov_b32_e32 v48, v2
	v_mov_b32_e32 v49, v2
	v_mov_b32_e32 v58, v2
	v_mov_b32_e32 v59, v2
	v_mov_b32_e32 v60, v2
	v_mov_b32_e32 v61, v2
	v_mov_b32_e32 v62, v2
	v_mov_b32_e32 v63, v2
	v_mov_b32_e32 v64, v2
	v_mov_b32_e32 v65, v2
	v_mov_b32_e32 v66, v2
	v_mov_b32_e32 v67, v2
	v_mov_b32_e32 v68, v2
	v_mov_b32_e32 v69, v2
	v_mov_b32_e32 v70, v2
	v_mov_b32_e32 v71, v2
	v_mov_b32_e32 v72, v2
	v_mov_b32_e32 v73, v2
	v_mov_b32_e32 v82, v2
	v_mov_b32_e32 v83, v2
	v_mov_b32_e32 v84, v2
	v_mov_b32_e32 v85, v2
	v_mov_b32_e32 v86, v2
	v_mov_b32_e32 v87, v2
	v_mov_b32_e32 v88, v2
	v_mov_b32_e32 v89, v2
	v_mov_b32_e32 v98, v2
	v_mov_b32_e32 v99, v2
	v_mov_b32_e32 v100, v2
	v_mov_b32_e32 v101, v2
	v_mov_b32_e32 v102, v2
	v_mov_b32_e32 v103, v2
	v_mov_b32_e32 v104, v2
	v_mov_b32_e32 v105, v2
	v_mov_b32_e32 v114, v2
	v_mov_b32_e32 v115, v2
	v_mov_b32_e32 v116, v2
	v_mov_b32_e32 v117, v2
	v_mov_b32_e32 v118, v2
	v_mov_b32_e32 v119, v2
	v_mov_b32_e32 v120, v2
	v_mov_b32_e32 v121, v2
	v_mov_b32_e32 v74, v2
	v_mov_b32_e32 v75, v2
	v_mov_b32_e32 v76, v2
	v_mov_b32_e32 v77, v2
	v_mov_b32_e32 v78, v2
	v_mov_b32_e32 v79, v2
	v_mov_b32_e32 v80, v2
	v_mov_b32_e32 v81, v2
	v_mov_b32_e32 v90, v2
	v_mov_b32_e32 v91, v2
	v_mov_b32_e32 v92, v2
	v_mov_b32_e32 v93, v2
	v_mov_b32_e32 v94, v2
	v_mov_b32_e32 v95, v2
	v_mov_b32_e32 v96, v2
	v_mov_b32_e32 v97, v2
	v_mov_b32_e32 v106, v2
	v_mov_b32_e32 v107, v2
	v_mov_b32_e32 v108, v2
	v_mov_b32_e32 v109, v2
	v_mov_b32_e32 v110, v2
	v_mov_b32_e32 v111, v2
	v_mov_b32_e32 v112, v2
	v_mov_b32_e32 v113, v2
	v_mov_b32_e32 v122, v2
	v_mov_b32_e32 v123, v2
	v_mov_b32_e32 v124, v2
	v_mov_b32_e32 v125, v2
	v_mov_b32_e32 v126, v2
	v_mov_b32_e32 v127, v2
	v_mov_b32_e32 v128, v2
	v_mov_b32_e32 v129, v2
	s_and_b64 vcc, exec, s[12:13]
	s_cbranch_vccz .Lsp_p11
	s_setprio 1

.LBB0_1165:
	s_add_u32 s6, s6, 0x158080
	s_addc_u32 s7, s7, 0
	s_add_u32 s8, s26, 0x100
	v_mov_b32_e32 v0, 0
	s_addc_u32 s9, s27, 0
	s_mov_b32 s55, -2
	v_mov_b32_e32 v1, v0
	v_mov_b32_e32 v2, v0
	v_mov_b32_e32 v3, v0
	v_mov_b32_e32 v4, v0
	v_mov_b32_e32 v5, v0
	v_mov_b32_e32 v6, v0
	v_mov_b32_e32 v7, v0
	v_mov_b32_e32 v16, v0
	v_mov_b32_e32 v17, v0
	v_mov_b32_e32 v18, v0
	v_mov_b32_e32 v19, v0
	v_mov_b32_e32 v20, v0
	v_mov_b32_e32 v21, v0
	v_mov_b32_e32 v22, v0
	v_mov_b32_e32 v23, v0
	v_mov_b32_e32 v32, v0
	v_mov_b32_e32 v33, v0
	v_mov_b32_e32 v34, v0
	v_mov_b32_e32 v35, v0
	v_mov_b32_e32 v36, v0
	v_mov_b32_e32 v37, v0
	v_mov_b32_e32 v38, v0
	v_mov_b32_e32 v39, v0
	v_mov_b32_e32 v48, v0
	v_mov_b32_e32 v49, v0
	v_mov_b32_e32 v50, v0
	v_mov_b32_e32 v51, v0
	v_mov_b32_e32 v52, v0
	v_mov_b32_e32 v53, v0
	v_mov_b32_e32 v54, v0
	v_mov_b32_e32 v55, v0
	v_mov_b32_e32 v8, v0
	v_mov_b32_e32 v9, v0
	v_mov_b32_e32 v10, v0
	v_mov_b32_e32 v11, v0
	v_mov_b32_e32 v12, v0
	v_mov_b32_e32 v13, v0
	v_mov_b32_e32 v14, v0
	v_mov_b32_e32 v15, v0
	v_mov_b32_e32 v24, v0
	v_mov_b32_e32 v25, v0
	v_mov_b32_e32 v26, v0
	v_mov_b32_e32 v27, v0
	v_mov_b32_e32 v28, v0
	v_mov_b32_e32 v29, v0
	v_mov_b32_e32 v30, v0
	v_mov_b32_e32 v31, v0
	v_mov_b32_e32 v40, v0
	v_mov_b32_e32 v41, v0
	v_mov_b32_e32 v42, v0
	v_mov_b32_e32 v43, v0
	v_mov_b32_e32 v44, v0
	v_mov_b32_e32 v45, v0
	v_mov_b32_e32 v46, v0
	v_mov_b32_e32 v47, v0
	v_mov_b32_e32 v56, v0
	v_mov_b32_e32 v57, v0
	v_mov_b32_e32 v58, v0
	v_mov_b32_e32 v59, v0
	v_mov_b32_e32 v60, v0
	v_mov_b32_e32 v61, v0
	v_mov_b32_e32 v62, v0
	v_mov_b32_e32 v63, v0
	v_mov_b32_e32 v64, v0
	v_mov_b32_e32 v65, v0
	v_mov_b32_e32 v66, v0
	v_mov_b32_e32 v67, v0
	v_mov_b32_e32 v68, v0
	v_mov_b32_e32 v69, v0
	v_mov_b32_e32 v70, v0
	v_mov_b32_e32 v71, v0
	v_mov_b32_e32 v80, v0
	v_mov_b32_e32 v81, v0
	v_mov_b32_e32 v82, v0
	v_mov_b32_e32 v83, v0
	v_mov_b32_e32 v84, v0
	v_mov_b32_e32 v85, v0
	v_mov_b32_e32 v86, v0
	v_mov_b32_e32 v87, v0
	v_mov_b32_e32 v96, v0
	v_mov_b32_e32 v97, v0
	v_mov_b32_e32 v98, v0
	v_mov_b32_e32 v99, v0
	v_mov_b32_e32 v100, v0
	v_mov_b32_e32 v101, v0
	v_mov_b32_e32 v102, v0
	v_mov_b32_e32 v103, v0
	v_mov_b32_e32 v128, v0
	v_mov_b32_e32 v129, v0
	v_mov_b32_e32 v130, v0
	v_mov_b32_e32 v131, v0
	v_mov_b32_e32 v132, v0
	v_mov_b32_e32 v133, v0
	v_mov_b32_e32 v134, v0
	v_mov_b32_e32 v135, v0
	v_mov_b32_e32 v72, v0
	v_mov_b32_e32 v73, v0
	v_mov_b32_e32 v74, v0
	v_mov_b32_e32 v75, v0
	v_mov_b32_e32 v76, v0
	v_mov_b32_e32 v77, v0
	v_mov_b32_e32 v78, v0
	v_mov_b32_e32 v79, v0
	v_mov_b32_e32 v88, v0
	v_mov_b32_e32 v89, v0
	v_mov_b32_e32 v90, v0
	v_mov_b32_e32 v91, v0
	v_mov_b32_e32 v92, v0
	v_mov_b32_e32 v93, v0
	v_mov_b32_e32 v94, v0
	v_mov_b32_e32 v95, v0
	v_mov_b32_e32 v116, v0
	v_mov_b32_e32 v117, v0
	v_mov_b32_e32 v118, v0
	v_mov_b32_e32 v119, v0
	v_mov_b32_e32 v124, v0
	v_mov_b32_e32 v125, v0
	v_mov_b32_e32 v126, v0
	v_mov_b32_e32 v127, v0
	v_mov_b32_e32 v136, v0
	v_mov_b32_e32 v137, v0
	v_mov_b32_e32 v138, v0
	v_mov_b32_e32 v139, v0
	v_mov_b32_e32 v140, v0
	v_mov_b32_e32 v141, v0
	v_mov_b32_e32 v142, v0
	v_mov_b32_e32 v143, v0
	s_and_b64 vcc, exec, s[18:19]
	s_cbranch_vccz .Lsp_p13
	s_setprio 1
